# code placement: the three GEMM K-loop heads padded to 64-byte boundaries with never-executed nops
# speedup vs baseline: 1.0085x; 1.0085x over previous
.LBB0_473:
	s_and_b32 s37, s5, 3
	s_lshr_b32 s38, s4, 6
	s_lshl_b32 s4, s1, 13
	s_lshl_b32 s5, s37, 12
	v_readlane_b32 s40, v253, 53
	v_readlane_b32 s6, v254, 42
	v_readlane_b32 s41, v253, 54
	v_readlane_b32 s7, v254, 43
	s_add_u32 s6, s40, s6
	s_addc_u32 s7, s41, s7
	v_readlane_b32 s18, v254, 29
	s_cmp_eq_u32 s18, 2
	s_cselect_b32 s17, s7, s23
	s_cselect_b32 s16, s6, s22
	s_cmp_lg_u32 s18, 18
	s_cselect_b64 s[18:19], -1, 0
	s_add_i32 m0, s31, 0x18000
	v_lshl_add_u64 v[4:5], v[4:5], 0, s[78:79]
	s_waitcnt vmcnt(2)
	s_barrier
	global_load_lds_dwordx4 v[4:5], off
	v_lshl_add_u64 v[4:5], v[6:7], 0, s[78:79]
	s_add_i32 m0, s31, 0x1a000
	s_add_i32 s39, s31, 0x8000
	global_load_lds_dwordx4 v[4:5], off
	v_lshl_add_u64 v[4:5], v[12:13], 0, s[78:79]
	s_mov_b32 m0, s39
	s_add_i32 s40, s31, 0xa000
	global_load_lds_dwordx4 v[4:5], off
	v_lshl_add_u64 v[4:5], v[14:15], 0, s[78:79]
	s_mov_b32 m0, s40
	s_add_i32 s41, s38, -2
	global_load_lds_dwordx4 v[4:5], off
	s_add_i32 m0, s31, 0x1c000
	v_lshl_add_u64 v[4:5], v[8:9], 0, s[78:79]
	global_load_lds_dwordx4 v[4:5], off
	v_lshl_add_u64 v[4:5], v[10:11], 0, s[78:79]
	s_add_i32 m0, s31, 0x1e000
	v_readlane_b32 s42, v253, 55
	global_load_lds_dwordx4 v[4:5], off
	v_bfe_u32 v4, v16, 4, 2
	v_and_b32_e32 v5, 15, v16
	v_lshlrev_b32_e32 v7, 4, v4
	v_lshl_or_b32 v175, s1, 6, v5
	v_lshl_or_b32 v5, v5, 6, v7
	v_lshlrev_b32_e32 v7, 2, v16
	v_and_b32_e32 v7, 32, v7
	v_bitop3_b32 v8, v5, s4, v7 bitop3:0xde
	v_bitop3_b32 v223, v5, s5, v7 bitop3:0xde
	v_readlane_b32 s4, v254, 27
	v_readlane_b32 s5, v254, 28
	v_lshlrev_b32_e32 v6, 3, v4
	v_mov_b32_e32 v5, v3
	v_cndmask_b32_e64 v188, 1.0, 0.5, s[4:5]
	v_cmp_eq_u32_e64 s[4:5], 0, v4
	v_add_u32_e32 v4, v22, v20
	v_add_lshl_u32 v4, v4, v21, 1
	s_waitcnt vmcnt(6)
	v_lshl_add_u64 v[192:193], s[12:13], 0, v[4:5]
	v_add_u32_e32 v4, v19, v17
	v_readlane_b32 s43, v253, 56
	v_readlane_b32 s45, v253, 58
	v_readlane_b32 s52, v254, 1
	v_readlane_b32 s53, v254, 2
	s_cmpk_lt_u32 s0, 0x100
	v_add_lshl_u32 v4, v4, v18, 1
	v_readlane_b32 s44, v253, 57
	v_lshl_or_b32 v224, s37, 5, v6
	s_cselect_b64 s[52:53], -1, 0
	s_mov_b32 s42, 0
	s_waitcnt lgkmcnt(0)
	s_ashr_i32 s43, s26, 31
	v_mov_b32_e32 v190, v188
	v_mov_b32_e32 v191, v188
	v_lshl_add_u64 v[194:195], s[12:13], 0, v[4:5]
	v_add_u32_e32 v225, 0, v8
	v_readlane_b32 s20, v253, 15
	v_readlane_b32 s45, v253, 14
	v_readlane_b32 s46, v253, 59
	v_readlane_b32 s47, v253, 60
	v_readlane_b32 s48, v253, 61
	v_readlane_b32 s49, v253, 62
	v_readlane_b32 s50, v253, 63
	v_readlane_b32 s51, v254, 0
	v_readlane_b32 s54, v254, 3
	v_readlane_b32 s55, v254, 4
	s_barrier
	s_branch .LBB0_476
	s_nop 0
	s_nop 0

.LBB0_585:
	v_lshl_add_u64 v[12:13], s[22:23], 0, v[2:3]
	v_mov_b32_e32 v1, v3
	s_lshl_b32 s6, s6, 5
	v_lshl_add_u64 v[14:15], s[22:23], 0, v[0:1]
	v_mov_b32_e32 v135, v3
	s_and_b32 s9, s6, 0x60
	s_add_i32 m0, s31, 0x18000
	v_lshl_add_u64 v[12:13], v[12:13], 0, s[78:79]
	v_lshl_add_u64 v[16:17], s[16:17], 0, v[134:135]
	v_mov_b32_e32 v133, v3
	s_lshl_b32 s8, s5, 13
	s_lshl_b32 s10, s9, 7
	s_waitcnt vmcnt(2)
	s_barrier
	global_load_lds_dwordx4 v[12:13], off
	v_lshl_add_u64 v[12:13], v[14:15], 0, s[78:79]
	s_add_i32 m0, s31, 0x1a000
	s_add_i32 s37, s31, 0x8000
	s_add_i32 s38, s31, 0xa000
	v_lshl_add_u64 v[18:19], s[16:17], 0, v[132:133]
	global_load_lds_dwordx4 v[12:13], off
	v_lshl_add_u64 v[12:13], v[16:17], 0, s[78:79]
	s_mov_b32 m0, s37
	s_add_u32 s6, s22, 0x40080
	global_load_lds_dwordx4 v[12:13], off
	v_lshl_add_u64 v[12:13], v[18:19], 0, s[78:79]
	s_mov_b32 m0, s38
	s_addc_u32 s7, s23, 0
	global_load_lds_dwordx4 v[12:13], off
	s_add_i32 m0, s31, 0x1c000
	v_lshl_add_u64 v[12:13], s[6:7], 0, v[2:3]
	global_load_lds_dwordx4 v[12:13], off
	v_lshl_add_u64 v[12:13], s[6:7], 0, v[0:1]
	s_add_i32 m0, s31, 0x1e000
	v_and_b32_e32 v11, 15, v4
	global_load_lds_dwordx4 v[12:13], off
	v_lshrrev_b32_e32 v12, 1, v4
	v_and_b32_e32 v12, 24, v12
	v_lshlrev_b32_e32 v13, 1, v12
	v_lshlrev_b32_e32 v4, 2, v4
	v_lshl_or_b32 v150, s5, 6, v11
	v_lshl_or_b32 v11, v11, 6, v13
	v_and_b32_e32 v4, 32, v4
	v_bitop3_b32 v13, v11, s8, v4 bitop3:0xde
	v_bitop3_b32 v151, v11, s10, v4 bitop3:0xde
	v_lshlrev_b32_e32 v4, 14, v9
	v_and_b32_e32 v4, 0xffff8000, v4
	v_lshl_add_u32 v4, v8, 11, v4
	v_and_b32_e32 v8, 1, v9
	v_lshl_or_b32 v4, v8, 6, v4
	v_lshl_add_u32 v136, v10, 1, v4
	v_lshlrev_b32_e32 v4, 14, v5
	v_and_b32_e32 v4, 0xffff8000, v4
	s_waitcnt vmcnt(6)
	v_lshl_add_u32 v4, v6, 11, v4
	v_and_b32_e32 v5, 1, v5
	s_cmpk_lt_u32 s4, 0x100
	v_lshl_or_b32 v4, v5, 6, v4
	v_readlane_b32 s4, v252, 33
	s_cselect_b64 s[6:7], -1, 0
	v_or_b32_e32 v152, s9, v12
	v_mov_b32_e32 v137, v3
	v_lshl_add_u32 v138, v7, 1, v4
	v_mov_b32_e32 v139, v3
	s_mov_b32 s39, 0
	v_add_u32_e32 v153, 0, v13
	v_readlane_b32 s40, v252, 32
	s_mov_b32 s41, s4
	s_barrier
	v_readlane_b32 s5, v252, 34
	s_branch .LBB0_588
	s_nop 0
	s_nop 0
	s_nop 0
	s_nop 0
	s_nop 0
